# code placement: GU GEMM K-loop top aligned to 64 bytes (20 bytes of padding before it)
# speedup vs baseline: 1.0041x; 1.0041x over previous
.LBB0_959:
	s_ashr_i32 s11, s10, 31
	s_lshl_b64 s[12:13], s[10:11], 19
	s_add_u32 s12, s29, s12
	s_addc_u32 s13, s19, s13
	s_and_b64 s[16:17], s[2:3], exec
	s_cselect_b32 s11, s13, s25
	s_cselect_b32 s67, s12, s24
	s_ashr_i32 s7, s6, 31
	s_lshl_b64 s[16:17], s[6:7], 19
	s_add_u32 s16, s30, s16
	s_addc_u32 s17, s31, s17
	s_and_b64 s[26:27], s[2:3], exec
	s_cselect_b32 s7, s17, s21
	s_cselect_b32 s68, s16, s20
	s_add_u32 s69, s20, 0x100
	s_addc_u32 s70, s21, 0
	s_add_u32 s20, s24, 0x40080
	v_mov_b32_e32 v2, 0
	s_addc_u32 s21, s25, 0
	s_mov_b32 s71, -2
	v_mov_b32_e32 v3, v2
	v_mov_b32_e32 v4, v2
	v_mov_b32_e32 v5, v2
	v_mov_b32_e32 v10, v2
	v_mov_b32_e32 v11, v2
	v_mov_b32_e32 v12, v2
	v_mov_b32_e32 v13, v2
	v_mov_b32_e32 v18, v2
	v_mov_b32_e32 v19, v2
	v_mov_b32_e32 v20, v2
	v_mov_b32_e32 v21, v2
	v_mov_b32_e32 v26, v2
	v_mov_b32_e32 v27, v2
	v_mov_b32_e32 v28, v2
	v_mov_b32_e32 v29, v2
	v_mov_b32_e32 v34, v2
	v_mov_b32_e32 v35, v2
	v_mov_b32_e32 v36, v2
	v_mov_b32_e32 v37, v2
	v_mov_b32_e32 v42, v2
	v_mov_b32_e32 v43, v2
	v_mov_b32_e32 v44, v2
	v_mov_b32_e32 v45, v2
	v_mov_b32_e32 v50, v2
	v_mov_b32_e32 v51, v2
	v_mov_b32_e32 v52, v2
	v_mov_b32_e32 v53, v2
	v_mov_b32_e32 v58, v2
	v_mov_b32_e32 v59, v2
	v_mov_b32_e32 v60, v2
	v_mov_b32_e32 v61, v2
	v_mov_b32_e32 v6, v2
	v_mov_b32_e32 v7, v2
	v_mov_b32_e32 v8, v2
	v_mov_b32_e32 v9, v2
	v_mov_b32_e32 v14, v2
	v_mov_b32_e32 v15, v2
	v_mov_b32_e32 v16, v2
	v_mov_b32_e32 v17, v2
	v_mov_b32_e32 v22, v2
	v_mov_b32_e32 v23, v2
	v_mov_b32_e32 v24, v2
	v_mov_b32_e32 v25, v2
	v_mov_b32_e32 v30, v2
	v_mov_b32_e32 v31, v2
	v_mov_b32_e32 v32, v2
	v_mov_b32_e32 v33, v2
	v_mov_b32_e32 v38, v2
	v_mov_b32_e32 v39, v2
	v_mov_b32_e32 v40, v2
	v_mov_b32_e32 v41, v2
	v_mov_b32_e32 v46, v2
	v_mov_b32_e32 v47, v2
	v_mov_b32_e32 v48, v2
	v_mov_b32_e32 v49, v2
	v_mov_b32_e32 v54, v2
	v_mov_b32_e32 v55, v2
	v_mov_b32_e32 v56, v2
	v_mov_b32_e32 v57, v2
	v_mov_b32_e32 v62, v2
	v_mov_b32_e32 v63, v2
	v_mov_b32_e32 v64, v2
	v_mov_b32_e32 v65, v2
	v_mov_b32_e32 v66, v2
	v_mov_b32_e32 v67, v2
	v_mov_b32_e32 v68, v2
	v_mov_b32_e32 v69, v2
	v_mov_b32_e32 v74, v2
	v_mov_b32_e32 v75, v2
	v_mov_b32_e32 v76, v2
	v_mov_b32_e32 v77, v2
	v_mov_b32_e32 v82, v2
	v_mov_b32_e32 v83, v2
	v_mov_b32_e32 v84, v2
	v_mov_b32_e32 v85, v2
	v_mov_b32_e32 v90, v2
	v_mov_b32_e32 v91, v2
	v_mov_b32_e32 v92, v2
	v_mov_b32_e32 v93, v2
	v_mov_b32_e32 v98, v2
	v_mov_b32_e32 v99, v2
	v_mov_b32_e32 v100, v2
	v_mov_b32_e32 v101, v2
	v_mov_b32_e32 v106, v2
	v_mov_b32_e32 v107, v2
	v_mov_b32_e32 v108, v2
	v_mov_b32_e32 v109, v2
	v_mov_b32_e32 v114, v2
	v_mov_b32_e32 v115, v2
	v_mov_b32_e32 v116, v2
	v_mov_b32_e32 v117, v2
	v_mov_b32_e32 v122, v2
	v_mov_b32_e32 v123, v2
	v_mov_b32_e32 v124, v2
	v_mov_b32_e32 v125, v2
	v_mov_b32_e32 v70, v2
	v_mov_b32_e32 v71, v2
	v_mov_b32_e32 v72, v2
	v_mov_b32_e32 v73, v2
	v_mov_b32_e32 v78, v2
	v_mov_b32_e32 v79, v2
	v_mov_b32_e32 v80, v2
	v_mov_b32_e32 v81, v2
	v_mov_b32_e32 v86, v2
	v_mov_b32_e32 v87, v2
	v_mov_b32_e32 v88, v2
	v_mov_b32_e32 v89, v2
	v_mov_b32_e32 v94, v2
	v_mov_b32_e32 v95, v2
	v_mov_b32_e32 v96, v2
	v_mov_b32_e32 v97, v2
	v_mov_b32_e32 v102, v2
	v_mov_b32_e32 v103, v2
	v_mov_b32_e32 v104, v2
	v_mov_b32_e32 v105, v2
	v_mov_b32_e32 v110, v2
	v_mov_b32_e32 v111, v2
	v_mov_b32_e32 v112, v2
	v_mov_b32_e32 v113, v2
	v_mov_b32_e32 v118, v2
	v_mov_b32_e32 v119, v2
	v_mov_b32_e32 v120, v2
	v_mov_b32_e32 v121, v2
	v_mov_b32_e32 v126, v2
	v_mov_b32_e32 v127, v2
	v_mov_b32_e32 v128, v2
	v_mov_b32_e32 v129, v2
	s_nop 0
	s_nop 0
	s_nop 0
	s_nop 0
	s_nop 0
	v_readfirstlane_b32 vcc_lo, v169
	s_nop 0
	s_bitcmp1_b32 vcc_lo, 8
	s_cbranch_scc0 .Lprio_skip_gu
	s_setprio 1
